# K-loop counted vmcnt re-derived per stage buffer (vmcnt(10) one phase before each read instead of vmcnt(6) at phases 4/8): 5 phases of load-latency tolerance; on top of v34
# speedup vs baseline: 1.0040x; 1.0040x over previous
; #define PG8_STAGE(bufoff, gbase) do { _Pragma("unroll") for (int _i = 0; _i < 2; ++_i) \
;         __builtin_amdgcn_global_load_lds((const unsigned*)((const char*)(gbase) + voff[_i]), (LAS unsigned*)(lds + (bufoff) + ldsw + _i * 8192), 16, 0, 0); } while (0)
; #define PG8_LDA(dst, b, h) do { _Pragma("unroll") for (int m = 0; m < 4; ++m) _Pragma("unroll") for (int k = 0; k < 2; ++k) dst[m][k] = *(const LAS bf16x8*)(lds + PG8_SA(b, h) + aoff + m * 2048 + k * 1024); } while (0)
; #define PG8_LDB(dst, b, h) do { _Pragma("unroll") for (int n = 0; n < 2; ++n) _Pragma("unroll") for (int k = 0; k < 2; ++k) dst[n][k] = *(const LAS bf16x8*)(lds + PG8_SB(b, h) + boff + n * 2048 + k * 1024); } while (0)
; #define PG8_MMA(ai, bj, At, Bt) do { __builtin_amdgcn_s_setprio(1); _Pragma("unroll") for (int m = 0; m < 4; ++m) _Pragma("unroll") for (int n = 0; n < 2; ++n) _Pragma("unroll") for (int k = 0; k < 2; ++k) \
;         acc[ai][bj][m][n] = __builtin_amdgcn_mfma_f32_16x16x32_bf16(Bt[n][k], At[m][k], acc[ai][bj][m][n], 0, 0, 0); __builtin_amdgcn_s_setprio(0); } while (0)
; #define PG8_WAIT_L(n) asm volatile("s_waitcnt lgkmcnt(" #n ")" ::: "memory")
; #define PG8_BAR __builtin_amdgcn_s_barrier()
; #define PG8_SCHED __builtin_amdgcn_sched_barrier(0)
; __device__ __forceinline__ void gemm_phase(const Params& p, LAS unsigned char* lds, int gph, unsigned ldB  ) {
;     ...
;     for (int t = 0; t < nt; t += 2) {
;       const bool last = (t == nt - 2);
;       const char* a1 = cA + (size_t)(t + 1) * kstep;
;       const char* a2 = last ? nA : cA + (size_t)(t + 2) * kstep; const char* b2 = last ? nB : cB + (size_t)(t + 2) * kstep;
;       const char* a3 = a2 + kstep; const char* b3 = b2 + kstep;
;       PG8_LDB(B0, 0, 0); PG8_SCHED; PG8_LDA(At, 0, 0); PG8_STAGE(PG8_SA(1, 1), a1 + hstep);
;       PG8_WAIT_L(8); PG8_BAR; PG8_WAIT_L(0); PG8_MMA(0, 0, At, B0); PG8_BAR; PG8_SCHED;
;       PG8_LDB(B1, 0, 1); PG8_STAGE(PG8_SB(0, 0), b2);
;       PG8_BAR; PG8_WAIT_L(0); PG8_MMA(0, 1, At, B1); PG8_BAR;
;       PG8_LDA(At, 0, 1); PG8_STAGE(PG8_SA(0, 0), a2);
;       PG8_BAR; PG8_WAIT_L(0); PG8_MMA(1, 0, At, B0); PG8_BAR; PG8_SCHED;
.LBB0_347:
	s_add_i32 s63, s38, 2
	s_add_u32 s40, s36, 0x80
	s_addc_u32 s39, s37, 0
	s_add_i32 s64, 0, 0x10000
	v_add_u32_e32 v64, s64, v175
	ds_read_b128 v[132:135], v64
	ds_read_b128 v[136:139], v64 offset:1024
	ds_read_b128 v[140:143], v64 offset:2048
	ds_read_b128 v[144:147], v64 offset:3072
	s_cmp_eq_u32 s60, s38
	s_cselect_b32 s38, s34, s40
	s_cselect_b32 s39, s29, s39
	s_cselect_b32 s41, s35, s62
	s_cselect_b32 s40, s49, s61
	v_lshl_add_u64 v[66:67], s[36:37], 0, v[192:193]
	s_add_i32 m0, s80, 0xc000
	ds_read_b128 v[148:151], v240
	ds_read_b128 v[152:155], v240 offset:1024
	ds_read_b128 v[156:159], v240 offset:2048
	ds_read_b128 v[160:163], v240 offset:3072
	ds_read_b128 v[164:167], v240 offset:4096
	ds_read_b128 v[196:199], v240 offset:5120
	ds_read_b128 v[200:203], v240 offset:6144
	ds_read_b128 v[204:207], v240 offset:7168
	global_load_lds_dwordx4 v[66:67], off
	v_lshl_add_u64 v[66:67], s[36:37], 0, v[194:195]
	s_add_i32 m0, s80, 0xe000
	s_nop 0
	global_load_lds_dwordx4 v[66:67], off
	s_waitcnt lgkmcnt(8)
	s_waitcnt vmcnt(10)
	s_barrier
	s_waitcnt lgkmcnt(0)
	s_setprio 1
	s_waitcnt lgkmcnt(0)
	v_mfma_f32_16x16x32_bf16 v[128:131], v[132:135], v[148:151], v[128:131]
	v_mfma_f32_16x16x32_bf16 v[124:127], v[140:143], v[148:151], v[124:127]
	v_mfma_f32_16x16x32_bf16 v[120:123], v[132:135], v[156:159], v[120:123]
	v_mfma_f32_16x16x32_bf16 v[116:119], v[140:143], v[156:159], v[116:119]
	v_mfma_f32_16x16x32_bf16 v[112:115], v[132:135], v[164:167], v[112:115]
	v_mfma_f32_16x16x32_bf16 v[108:111], v[140:143], v[164:167], v[108:111]
	v_mfma_f32_16x16x32_bf16 v[104:107], v[132:135], v[200:203], v[104:107]
	v_mfma_f32_16x16x32_bf16 v[100:103], v[140:143], v[200:203], v[100:103]
	v_mfma_f32_16x16x32_bf16 v[128:131], v[136:139], v[152:155], v[128:131]
	v_mfma_f32_16x16x32_bf16 v[124:127], v[144:147], v[152:155], v[124:127]
	v_mfma_f32_16x16x32_bf16 v[120:123], v[136:139], v[160:163], v[120:123]
	v_mfma_f32_16x16x32_bf16 v[116:119], v[144:147], v[160:163], v[116:119]
	v_mfma_f32_16x16x32_bf16 v[112:115], v[136:139], v[196:199], v[112:115]
	v_mfma_f32_16x16x32_bf16 v[108:111], v[144:147], v[196:199], v[108:111]
	v_mfma_f32_16x16x32_bf16 v[104:107], v[136:139], v[204:207], v[104:107]
	v_mfma_f32_16x16x32_bf16 v[100:103], v[144:147], v[204:207], v[100:103]
	s_setprio 0
	s_barrier
	s_add_i32 s65, 0, 0x14000
	s_add_i32 s64, s64, s79
	v_add_u32_e32 v64, s65, v175
	v_lshl_add_u64 v[224:225], s[40:41], 0, v[170:171]
	s_mov_b32 m0, s64
	ds_read_b128 v[208:211], v64
	ds_read_b128 v[212:215], v64 offset:1024
	ds_read_b128 v[216:219], v64 offset:2048
	ds_read_b128 v[220:223], v64 offset:3072
	global_load_lds_dwordx4 v[224:225], off
	v_lshl_add_u64 v[232:233], s[40:41], 0, v[172:173]
	s_add_i32 m0, s64, 0x2000
	s_nop 0
	global_load_lds_dwordx4 v[232:233], off
	s_waitcnt vmcnt(10)
	s_barrier
	s_waitcnt lgkmcnt(0)
	s_setprio 1
	s_waitcnt lgkmcnt(0)
	v_mfma_f32_16x16x32_bf16 v[96:99], v[208:211], v[148:151], v[96:99]
	v_mfma_f32_16x16x32_bf16 v[92:95], v[216:219], v[148:151], v[92:95]
	v_mfma_f32_16x16x32_bf16 v[88:91], v[208:211], v[156:159], v[88:91]
	v_mfma_f32_16x16x32_bf16 v[84:87], v[216:219], v[156:159], v[84:87]
	v_mfma_f32_16x16x32_bf16 v[80:83], v[208:211], v[164:167], v[80:83]
	v_mfma_f32_16x16x32_bf16 v[76:79], v[216:219], v[164:167], v[76:79]
	v_mfma_f32_16x16x32_bf16 v[72:75], v[208:211], v[200:203], v[72:75]
	v_mfma_f32_16x16x32_bf16 v[66:69], v[216:219], v[200:203], v[68:71]
	v_mfma_f32_16x16x32_bf16 v[96:99], v[212:215], v[152:155], v[96:99]
	v_mfma_f32_16x16x32_bf16 v[92:95], v[220:223], v[152:155], v[92:95]
	v_mfma_f32_16x16x32_bf16 v[88:91], v[212:215], v[160:163], v[88:91]
	v_mfma_f32_16x16x32_bf16 v[84:87], v[220:223], v[160:163], v[84:87]
	v_mfma_f32_16x16x32_bf16 v[80:83], v[212:215], v[196:199], v[80:83]
	v_mfma_f32_16x16x32_bf16 v[76:79], v[220:223], v[196:199], v[76:79]
	v_mfma_f32_16x16x32_bf16 v[72:75], v[212:215], v[204:207], v[72:75]
	v_mfma_f32_16x16x32_bf16 v[66:69], v[220:223], v[204:207], v[66:69]
	s_setprio 0
	s_mov_b32 m0, s80
	v_lshl_add_u64 v[234:235], s[38:39], 0, v[170:171]
	s_barrier
	ds_read_b128 v[148:151], v240 offset:16384
	ds_read_b128 v[152:155], v240 offset:17408
	ds_read_b128 v[156:159], v240 offset:18432
	ds_read_b128 v[160:163], v240 offset:19456
	ds_read_b128 v[164:167], v240 offset:20480
	ds_read_b128 v[196:199], v240 offset:21504
	ds_read_b128 v[200:203], v240 offset:22528
	ds_read_b128 v[204:207], v240 offset:23552
	global_load_lds_dwordx4 v[234:235], off
	v_lshl_add_u64 v[242:243], s[38:39], 0, v[172:173]
	s_mov_b32 m0, s81
	s_nop 0
	global_load_lds_dwordx4 v[242:243], off
	s_barrier
	s_waitcnt lgkmcnt(0)
	s_setprio 1
	s_waitcnt lgkmcnt(0)
	v_mfma_f32_16x16x32_bf16 v[60:63], v[132:135], v[148:151], v[60:63]
	v_mfma_f32_16x16x32_bf16 v[56:59], v[140:143], v[148:151], v[56:59]
	v_mfma_f32_16x16x32_bf16 v[52:55], v[132:135], v[156:159], v[52:55]
	v_mfma_f32_16x16x32_bf16 v[48:51], v[140:143], v[156:159], v[48:51]
	v_mfma_f32_16x16x32_bf16 v[44:47], v[132:135], v[164:167], v[44:47]
	v_mfma_f32_16x16x32_bf16 v[40:43], v[140:143], v[164:167], v[40:43]
	v_mfma_f32_16x16x32_bf16 v[36:39], v[132:135], v[200:203], v[36:39]
	v_mfma_f32_16x16x32_bf16 v[32:35], v[140:143], v[200:203], v[32:35]
	v_mfma_f32_16x16x32_bf16 v[60:63], v[136:139], v[152:155], v[60:63]
	v_mfma_f32_16x16x32_bf16 v[56:59], v[144:147], v[152:155], v[56:59]
	v_mfma_f32_16x16x32_bf16 v[52:55], v[136:139], v[160:163], v[52:55]
	v_mfma_f32_16x16x32_bf16 v[48:51], v[144:147], v[160:163], v[48:51]
	v_mfma_f32_16x16x32_bf16 v[44:47], v[136:139], v[196:199], v[44:47]
	v_mfma_f32_16x16x32_bf16 v[40:43], v[144:147], v[196:199], v[40:43]
	v_mfma_f32_16x16x32_bf16 v[36:39], v[136:139], v[204:207], v[36:39]
	v_mfma_f32_16x16x32_bf16 v[32:35], v[144:147], v[204:207], v[32:35]
	s_setprio 0
	s_barrier
; #define PG8_STAGE(bufoff, gbase) do { _Pragma("unroll") for (int _i = 0; _i < 2; ++_i) \
;         __builtin_amdgcn_global_load_lds((const unsigned*)((const char*)(gbase) + voff[_i]), (LAS unsigned*)(lds + (bufoff) + ldsw + _i * 8192), 16, 0, 0); } while (0)
; #define PG8_LDA(dst, b, h) do { _Pragma("unroll") for (int m = 0; m < 4; ++m) _Pragma("unroll") for (int k = 0; k < 2; ++k) dst[m][k] = *(const LAS bf16x8*)(lds + PG8_SA(b, h) + aoff + m * 2048 + k * 1024); } while (0)
; #define PG8_LDB(dst, b, h) do { _Pragma("unroll") for (int n = 0; n < 2; ++n) _Pragma("unroll") for (int k = 0; k < 2; ++k) dst[n][k] = *(const LAS bf16x8*)(lds + PG8_SB(b, h) + boff + n * 2048 + k * 1024); } while (0)
; #define PG8_MMA(ai, bj, At, Bt) do { __builtin_amdgcn_s_setprio(1); _Pragma("unroll") for (int m = 0; m < 4; ++m) _Pragma("unroll") for (int n = 0; n < 2; ++n) _Pragma("unroll") for (int k = 0; k < 2; ++k) \
;         acc[ai][bj][m][n] = __builtin_amdgcn_mfma_f32_16x16x32_bf16(Bt[n][k], At[m][k], acc[ai][bj][m][n], 0, 0, 0); __builtin_amdgcn_s_setprio(0); } while (0)
; #define PG8_WAIT_V(n) asm volatile("s_waitcnt vmcnt(" #n ")" ::: "memory")
; #define PG8_WAIT_L(n) asm volatile("s_waitcnt lgkmcnt(" #n ")" ::: "memory")
; #define PG8_BAR __builtin_amdgcn_s_barrier()
; #define PG8_SCHED __builtin_amdgcn_sched_barrier(0)
; __device__ __forceinline__ void gemm_phase(const Params& p, LAS unsigned char* lds, int gph, unsigned ldB  ) {
;     ...
;       PG8_BAR; PG8_WAIT_L(0); PG8_MMA(1, 0, At, B0); PG8_BAR; PG8_SCHED;
;       PG8_STAGE(PG8_SB(0, 1), b2 + hstep);
;       PG8_WAIT_V(6); PG8_BAR; PG8_MMA(1, 1, At, B1); PG8_BAR;
;       PG8_LDB(B0, 1, 0); PG8_SCHED; PG8_LDA(At, 1, 0); PG8_STAGE(PG8_SA(0, 1), a2 + hstep);
;       PG8_WAIT_L(8); PG8_BAR; PG8_WAIT_L(0); PG8_MMA(0, 0, At, B0); PG8_BAR; PG8_SCHED;
;       PG8_LDB(B1, 1, 1); PG8_STAGE(PG8_SB(1, 0), b3);
;       PG8_BAR; PG8_WAIT_L(0); PG8_MMA(0, 1, At, B1); PG8_BAR;
	s_add_u32 s40, s40, s50
	s_addc_u32 s41, s41, 0
	s_add_i32 s64, s65, s79
	v_lshl_add_u64 v[244:245], s[40:41], 0, v[170:171]
	s_mov_b32 m0, s64
	v_lshl_add_u64 v[246:247], s[40:41], 0, v[172:173]
	global_load_lds_dwordx4 v[244:245], off
	s_add_i32 m0, s64, 0x2000
	s_nop 0
	global_load_lds_dwordx4 v[246:247], off
	s_waitcnt vmcnt(10)
	s_barrier
	s_setprio 1
	v_mfma_f32_16x16x32_bf16 v[28:31], v[208:211], v[148:151], v[28:31]
	v_mfma_f32_16x16x32_bf16 v[24:27], v[216:219], v[148:151], v[24:27]
	v_mfma_f32_16x16x32_bf16 v[20:23], v[208:211], v[156:159], v[20:23]
	v_mfma_f32_16x16x32_bf16 v[16:19], v[216:219], v[156:159], v[16:19]
	v_mfma_f32_16x16x32_bf16 v[12:15], v[208:211], v[164:167], v[12:15]
	v_mfma_f32_16x16x32_bf16 v[8:11], v[216:219], v[164:167], v[8:11]
	v_mfma_f32_16x16x32_bf16 v[4:7], v[208:211], v[200:203], v[4:7]
	v_mfma_f32_16x16x32_bf16 v[0:3], v[216:219], v[200:203], v[0:3]
	v_mfma_f32_16x16x32_bf16 v[28:31], v[212:215], v[152:155], v[28:31]
	v_mfma_f32_16x16x32_bf16 v[24:27], v[220:223], v[152:155], v[24:27]
	v_mfma_f32_16x16x32_bf16 v[20:23], v[212:215], v[160:163], v[20:23]
	v_mfma_f32_16x16x32_bf16 v[16:19], v[220:223], v[160:163], v[16:19]
	v_mfma_f32_16x16x32_bf16 v[12:15], v[212:215], v[196:199], v[12:15]
	v_mfma_f32_16x16x32_bf16 v[8:11], v[220:223], v[196:199], v[8:11]
	v_mfma_f32_16x16x32_bf16 v[4:7], v[212:215], v[204:207], v[4:7]
	v_mfma_f32_16x16x32_bf16 v[0:3], v[220:223], v[204:207], v[0:3]
	s_setprio 0
	s_add_i32 s40, 0, 0x18000
	v_add_u32_e32 v64, s40, v175
	s_barrier
	ds_read_b128 v[132:135], v64
	ds_read_b128 v[136:139], v64 offset:1024
	ds_read_b128 v[140:143], v64 offset:2048
	ds_read_b128 v[144:147], v64 offset:3072
	s_add_u32 s38, s38, s50
	s_addc_u32 s39, s39, 0
	s_mov_b32 m0, s82
	v_lshl_add_u64 v[70:71], s[38:39], 0, v[170:171]
	ds_read_b128 v[148:151], v240 offset:32768
	ds_read_b128 v[152:155], v240 offset:33792
	ds_read_b128 v[156:159], v240 offset:34816
	ds_read_b128 v[160:163], v240 offset:35840
	ds_read_b128 v[164:167], v240 offset:36864
	ds_read_b128 v[196:199], v240 offset:37888
	ds_read_b128 v[200:203], v240 offset:38912
	ds_read_b128 v[204:207], v240 offset:39936
	global_load_lds_dwordx4 v[70:71], off
	v_lshl_add_u64 v[70:71], s[38:39], 0, v[172:173]
	s_mov_b32 m0, s83
	s_nop 0
	global_load_lds_dwordx4 v[70:71], off
	s_waitcnt lgkmcnt(8)
	s_waitcnt vmcnt(10)
	s_barrier
	s_waitcnt lgkmcnt(0)
	s_setprio 1
	s_waitcnt lgkmcnt(0)
	v_mfma_f32_16x16x32_bf16 v[128:131], v[132:135], v[148:151], v[128:131]
	v_mfma_f32_16x16x32_bf16 v[124:127], v[140:143], v[148:151], v[124:127]
	v_mfma_f32_16x16x32_bf16 v[120:123], v[132:135], v[156:159], v[120:123]
	v_mfma_f32_16x16x32_bf16 v[116:119], v[140:143], v[156:159], v[116:119]
	v_mfma_f32_16x16x32_bf16 v[112:115], v[132:135], v[164:167], v[112:115]
	v_mfma_f32_16x16x32_bf16 v[108:111], v[140:143], v[164:167], v[108:111]
	v_mfma_f32_16x16x32_bf16 v[104:107], v[132:135], v[200:203], v[104:107]
	v_mfma_f32_16x16x32_bf16 v[100:103], v[140:143], v[200:203], v[100:103]
	v_mfma_f32_16x16x32_bf16 v[128:131], v[136:139], v[152:155], v[128:131]
	v_mfma_f32_16x16x32_bf16 v[124:127], v[144:147], v[152:155], v[124:127]
	v_mfma_f32_16x16x32_bf16 v[120:123], v[136:139], v[160:163], v[120:123]
	v_mfma_f32_16x16x32_bf16 v[116:119], v[144:147], v[160:163], v[116:119]
	v_mfma_f32_16x16x32_bf16 v[112:115], v[136:139], v[196:199], v[112:115]
	v_mfma_f32_16x16x32_bf16 v[108:111], v[144:147], v[196:199], v[108:111]
	v_mfma_f32_16x16x32_bf16 v[104:107], v[136:139], v[204:207], v[104:107]
	v_mfma_f32_16x16x32_bf16 v[100:103], v[144:147], v[204:207], v[100:103]
	s_setprio 0
	s_barrier
	s_add_i32 s38, 0, 0x1c000
	s_add_i32 s39, s40, s79
	v_add_u32_e32 v64, s38, v175
	v_lshl_add_u64 v[70:71], v[224:225], 0, s[0:1]
	s_mov_b32 m0, s39
	ds_read_b128 v[208:211], v64
	ds_read_b128 v[212:215], v64 offset:1024
	ds_read_b128 v[216:219], v64 offset:2048
	ds_read_b128 v[220:223], v64 offset:3072
	global_load_lds_dwordx4 v[70:71], off
	v_lshl_add_u64 v[70:71], v[232:233], 0, s[0:1]
	s_add_i32 m0, s39, 0x2000
	s_nop 0
	global_load_lds_dwordx4 v[70:71], off
	s_waitcnt vmcnt(10)
	s_barrier
; #define PG8_STAGE(bufoff, gbase) do { _Pragma("unroll") for (int _i = 0; _i < 2; ++_i) \
;         __builtin_amdgcn_global_load_lds((const unsigned*)((const char*)(gbase) + voff[_i]), (LAS unsigned*)(lds + (bufoff) + ldsw + _i * 8192), 16, 0, 0); } while (0)
; #define PG8_LDA(dst, b, h) do { _Pragma("unroll") for (int m = 0; m < 4; ++m) _Pragma("unroll") for (int k = 0; k < 2; ++k) dst[m][k] = *(const LAS bf16x8*)(lds + PG8_SA(b, h) + aoff + m * 2048 + k * 1024); } while (0)
; #define PG8_MMA(ai, bj, At, Bt) do { __builtin_amdgcn_s_setprio(1); _Pragma("unroll") for (int m = 0; m < 4; ++m) _Pragma("unroll") for (int n = 0; n < 2; ++n) _Pragma("unroll") for (int k = 0; k < 2; ++k) \
;         acc[ai][bj][m][n] = __builtin_amdgcn_mfma_f32_16x16x32_bf16(Bt[n][k], At[m][k], acc[ai][bj][m][n], 0, 0, 0); __builtin_amdgcn_s_setprio(0); } while (0)
; #define PG8_WAIT_V(n) asm volatile("s_waitcnt vmcnt(" #n ")" ::: "memory")
; #define PG8_WAIT_L(n) asm volatile("s_waitcnt lgkmcnt(" #n ")" ::: "memory")
; #define PG8_BAR __builtin_amdgcn_s_barrier()
; #define PG8_SCHED __builtin_amdgcn_sched_barrier(0)
; __device__ __forceinline__ void gemm_phase(const Params& p, LAS unsigned char* lds, int gph, unsigned ldB  ) {
;     ...
;       PG8_BAR; PG8_WAIT_L(0); PG8_MMA(0, 1, At, B1); PG8_BAR;
;       PG8_LDA(At, 1, 1); PG8_STAGE(PG8_SA(1, 0), a3);
;       PG8_BAR; PG8_WAIT_L(0); PG8_MMA(1, 0, At, B0); PG8_BAR; PG8_SCHED;
;       PG8_STAGE(PG8_SB(1, 1), b3 + hstep);
;       PG8_WAIT_V(6); PG8_BAR; PG8_MMA(1, 1, At, B1); PG8_BAR;
;     }
	s_waitcnt lgkmcnt(0)
	s_setprio 1
	s_waitcnt lgkmcnt(0)
	v_mfma_f32_16x16x32_bf16 v[96:99], v[208:211], v[148:151], v[96:99]
	v_mfma_f32_16x16x32_bf16 v[92:95], v[216:219], v[148:151], v[92:95]
	v_mfma_f32_16x16x32_bf16 v[88:91], v[208:211], v[156:159], v[88:91]
	v_mfma_f32_16x16x32_bf16 v[84:87], v[216:219], v[156:159], v[84:87]
	v_mfma_f32_16x16x32_bf16 v[80:83], v[208:211], v[164:167], v[80:83]
	v_mfma_f32_16x16x32_bf16 v[76:79], v[216:219], v[164:167], v[76:79]
	v_mfma_f32_16x16x32_bf16 v[70:73], v[208:211], v[200:203], v[72:75]
	v_mfma_f32_16x16x32_bf16 v[66:69], v[216:219], v[200:203], v[66:69]
	v_mfma_f32_16x16x32_bf16 v[96:99], v[212:215], v[152:155], v[96:99]
	v_mfma_f32_16x16x32_bf16 v[92:95], v[220:223], v[152:155], v[92:95]
	v_mfma_f32_16x16x32_bf16 v[88:91], v[212:215], v[160:163], v[88:91]
	v_mfma_f32_16x16x32_bf16 v[84:87], v[220:223], v[160:163], v[84:87]
	v_mfma_f32_16x16x32_bf16 v[80:83], v[212:215], v[196:199], v[80:83]
	v_mfma_f32_16x16x32_bf16 v[76:79], v[220:223], v[196:199], v[76:79]
	v_mfma_f32_16x16x32_bf16 v[72:75], v[212:215], v[204:207], v[70:73]
	v_mfma_f32_16x16x32_bf16 v[68:71], v[220:223], v[204:207], v[66:69]
	s_setprio 0
	s_mov_b32 m0, s84
	s_nop 0
	v_lshl_add_u64 v[66:67], v[234:235], 0, s[0:1]
	s_barrier
	ds_read_b128 v[148:151], v240 offset:49152
	ds_read_b128 v[152:155], v240 offset:50176
	ds_read_b128 v[156:159], v240 offset:51200
	ds_read_b128 v[160:163], v240 offset:52224
	ds_read_b128 v[164:167], v240 offset:53248
	ds_read_b128 v[196:199], v240 offset:54272
	ds_read_b128 v[200:203], v240 offset:55296
	ds_read_b128 v[204:207], v240 offset:56320
	global_load_lds_dwordx4 v[66:67], off
	v_lshl_add_u64 v[66:67], v[242:243], 0, s[0:1]
	s_mov_b32 m0, s85
	s_nop 0
	global_load_lds_dwordx4 v[66:67], off
	s_barrier
	s_waitcnt lgkmcnt(0)
	s_setprio 1
	s_waitcnt lgkmcnt(0)
	v_mfma_f32_16x16x32_bf16 v[60:63], v[132:135], v[148:151], v[60:63]
	v_mfma_f32_16x16x32_bf16 v[56:59], v[140:143], v[148:151], v[56:59]
	v_mfma_f32_16x16x32_bf16 v[52:55], v[132:135], v[156:159], v[52:55]
	v_mfma_f32_16x16x32_bf16 v[48:51], v[140:143], v[156:159], v[48:51]
	v_mfma_f32_16x16x32_bf16 v[44:47], v[132:135], v[164:167], v[44:47]
	v_mfma_f32_16x16x32_bf16 v[40:43], v[140:143], v[164:167], v[40:43]
	v_mfma_f32_16x16x32_bf16 v[36:39], v[132:135], v[200:203], v[36:39]
	v_mfma_f32_16x16x32_bf16 v[32:35], v[140:143], v[200:203], v[32:35]
	v_mfma_f32_16x16x32_bf16 v[60:63], v[136:139], v[152:155], v[60:63]
	v_mfma_f32_16x16x32_bf16 v[56:59], v[144:147], v[152:155], v[56:59]
	v_mfma_f32_16x16x32_bf16 v[52:55], v[136:139], v[160:163], v[52:55]
	v_mfma_f32_16x16x32_bf16 v[48:51], v[144:147], v[160:163], v[48:51]
	v_mfma_f32_16x16x32_bf16 v[44:47], v[136:139], v[196:199], v[44:47]
	v_mfma_f32_16x16x32_bf16 v[40:43], v[144:147], v[196:199], v[40:43]
	v_mfma_f32_16x16x32_bf16 v[36:39], v[136:139], v[204:207], v[36:39]
	v_mfma_f32_16x16x32_bf16 v[32:35], v[144:147], v[204:207], v[32:35]
	s_setprio 0
	s_barrier
	s_add_i32 s38, s38, s79
	v_lshl_add_u64 v[66:67], v[244:245], 0, s[0:1]
	s_mov_b32 m0, s38
	s_nop 0
	global_load_lds_dwordx4 v[66:67], off
	v_lshl_add_u64 v[66:67], v[246:247], 0, s[0:1]
	s_add_i32 m0, s38, 0x2000
	s_nop 0
	global_load_lds_dwordx4 v[66:67], off
	s_waitcnt vmcnt(10)
	s_barrier
	s_setprio 1
	v_mfma_f32_16x16x32_bf16 v[28:31], v[208:211], v[148:151], v[28:31]
	v_mfma_f32_16x16x32_bf16 v[24:27], v[216:219], v[148:151], v[24:27]
	v_mfma_f32_16x16x32_bf16 v[20:23], v[208:211], v[156:159], v[20:23]
	v_mfma_f32_16x16x32_bf16 v[16:19], v[216:219], v[156:159], v[16:19]
	v_mfma_f32_16x16x32_bf16 v[12:15], v[208:211], v[164:167], v[12:15]
	v_mfma_f32_16x16x32_bf16 v[8:11], v[216:219], v[164:167], v[8:11]
	v_mfma_f32_16x16x32_bf16 v[4:7], v[208:211], v[200:203], v[4:7]
	v_mfma_f32_16x16x32_bf16 v[0:3], v[216:219], v[200:203], v[0:3]
	v_mfma_f32_16x16x32_bf16 v[28:31], v[212:215], v[152:155], v[28:31]
	v_mfma_f32_16x16x32_bf16 v[24:27], v[220:223], v[152:155], v[24:27]
	v_mfma_f32_16x16x32_bf16 v[20:23], v[212:215], v[160:163], v[20:23]
	v_mfma_f32_16x16x32_bf16 v[16:19], v[220:223], v[160:163], v[16:19]
	v_mfma_f32_16x16x32_bf16 v[12:15], v[212:215], v[196:199], v[12:15]
	v_mfma_f32_16x16x32_bf16 v[8:11], v[220:223], v[196:199], v[8:11]
	v_mfma_f32_16x16x32_bf16 v[4:7], v[212:215], v[204:207], v[4:7]
	v_mfma_f32_16x16x32_bf16 v[0:3], v[220:223], v[204:207], v[0:3]
	s_setprio 0
	s_add_u32 s36, s36, 0x100
	s_addc_u32 s37, s37, 0
	s_add_u32 s61, s61, 0x100
	s_addc_u32 s62, s62, 0
	s_cmp_ge_i32 s63, s77
	s_mov_b32 s38, s63
	s_barrier
	s_cbranch_scc0 .LBB0_347
